# LRU priorities: conv/carry segments and the gate segment's flush + MFMA issue at s_setprio 1, only the gate transcendental math at 0
# baseline (speedup 1.0000x reference)
; #define LAS __attribute__((address_space(3)))
; template <int dir>
; __device__ __forceinline__ void lru_pass(LAS unsigned char* lds, const Params& P, int b, int h, int q, bool dry) {
;     ...
;             { const int sl = 32 * wid + s_i; const int tlA = dir == 0 ? sl : 255 - sl;
;               const LAS unsigned char* ap = XC + tlA * XC_PITCH + 16 * g;
;               const LAS unsigned char* wrp = WB + nl * XC_PITCH + 16 * g; const LAS unsigned char* wip = wrp + 32 * XC_PITCH;
; #pragma unroll
;               for (int ks = 0; ks < 8; ++ks) { const bf16x8 A = *(const LAS bf16x8*)(ap + 32 * ks);
;                   const bf16x8 Br = *(const LAS bf16x8*)(wrp + 32 * ks), Bi = *(const LAS bf16x8*)(wip + 32 * ks);
;                   zr = __builtin_amdgcn_mfma_f32_32x32x16_bf16(A, Br, zr, 0, 0, 0); zi = __builtin_amdgcn_mfma_f32_32x32x16_bf16(A, Bi, zi, 0, 0, 0); } }
;             unsigned xcb[16], pk[16];
; #pragma unroll
;             for (int v = 0; v < 16; ++v) { const int s = sbase + v; const int tl = dir == 0 ? s : 255 - s; xcb[v] = *(const LAS bf16_t*)(XC + tl * XC_PITCH + chl * 2);
;                 if (dir == 0) pk[v] = *(const LAS bf16_t*)(TIN + tl * IO_NP + nl * 2); else pk[v] = *(const LAS unsigned*)(TIN + tl * IO_WP + nl * 4); }
;             float Pp = 1.f, E = 0.f;
; #pragma unroll
;             for (int v = 0; v < 16; ++v) {
;                 const float xcv = __uint_as_float(xcb[v] << 16);
;                 const float r = __builtin_amdgcn_rcpf(1.0f + __builtin_amdgcn_exp2f(zr[v]));
;                 const float ig = __builtin_amdgcn_rcpf(1.0f + __builtin_amdgcn_exp2f(zi[v]));
;                 const float a = __builtin_amdgcn_exp2f(cl * r);
;                 const float sq = __builtin_amdgcn_sqrtf(fmaf(-a, a, 1.0f));
;                 const float u = sq * ig * xcv;
;                 E = fmaf(a, E, u); Pp *= a; zr[v] = E; zi[v] = Pp; }
.Llruf_wres:
	ds_read_b128 v[120:123], v160
	ds_read_b128 v[124:127], v160 offset:32
	ds_read_b128 v[168:171], v160 offset:64
	ds_read_b128 v[172:175], v160 offset:96
	ds_read_b128 v[176:179], v160 offset:128
	ds_read_b128 v[180:183], v160 offset:160
	ds_read_b128 v[184:187], v160 offset:192
	ds_read_b128 v[188:191], v160 offset:224
	ds_read_b128 v[236:239], v161 offset:8704
	ds_read_b128 v[240:243], v161 offset:8736
	ds_read_b128 v[244:247], v161 offset:8768
	ds_read_b128 v[248:251], v161 offset:8800
	s_waitcnt lgkmcnt(11)
	v_mfma_f32_32x32x16_bf16 v[32:47], v[120:123], v[204:207], v[0:15]
	s_waitcnt lgkmcnt(10)
	v_mfma_f32_32x32x16_bf16 v[32:47], v[124:127], v[208:211], v[32:47]
	s_waitcnt lgkmcnt(9)
	v_mfma_f32_32x32x16_bf16 v[32:47], v[168:171], v[212:215], v[32:47]
	s_waitcnt lgkmcnt(8)
	v_mfma_f32_32x32x16_bf16 v[32:47], v[172:175], v[216:219], v[32:47]
	s_waitcnt lgkmcnt(7)
	v_mfma_f32_32x32x16_bf16 v[32:47], v[176:179], v[220:223], v[32:47]
	s_waitcnt lgkmcnt(6)
	v_mfma_f32_32x32x16_bf16 v[32:47], v[180:183], v[224:227], v[32:47]
	s_waitcnt lgkmcnt(5)
	v_mfma_f32_32x32x16_bf16 v[32:47], v[184:187], v[228:231], v[32:47]
	s_waitcnt lgkmcnt(4)
	v_mfma_f32_32x32x16_bf16 v[32:47], v[188:191], v[232:235], v[32:47]
	s_waitcnt lgkmcnt(3)
	v_mfma_f32_32x32x16_bf16 v[48:63], v[120:123], v[236:239], v[16:31]
	ds_read_b128 v[236:239], v161 offset:8832
	s_setprio 0
	s_nop 8
	v_exp_f32_e32 v32, v32
	v_exp_f32_e32 v33, v33
	v_exp_f32_e32 v34, v34
	v_add_f32_e32 v32, 1.0, v32
	v_rcp_f32_e32 v32, v32
	s_waitcnt lgkmcnt(3)
	v_mfma_f32_32x32x16_bf16 v[48:63], v[124:127], v[240:243], v[48:63]
	ds_read_b128 v[240:243], v161 offset:8864
	v_add_f32_e32 v33, 1.0, v33
	v_mul_f32_e32 v32, v138, v32
	v_rcp_f32_e32 v33, v33
	s_nop 0
	v_mul_f32_e32 v33, v138, v33
	s_waitcnt lgkmcnt(3)
	v_mfma_f32_32x32x16_bf16 v[48:63], v[168:171], v[244:247], v[48:63]
	ds_read_b128 v[244:247], v161 offset:8896
	v_exp_f32_e32 v33, v33
	s_waitcnt lgkmcnt(3)
	v_mfma_f32_32x32x16_bf16 v[48:63], v[172:175], v[248:251], v[48:63]
	ds_read_b128 v[248:251], v161 offset:8928
	ds_read_u16 v152, v162
	ds_read_u16 v154, v162 offset:272
	ds_read_u16 v155, v162 offset:544
	ds_read_u16 v157, v162 offset:816
	ds_read_u16 v196, v162 offset:1088
	ds_read_u16 v197, v162 offset:1360
	s_waitcnt lgkmcnt(5)
	v_lshlrev_b32_e32 v152, 16, v152
	s_waitcnt lgkmcnt(4)
	v_lshlrev_b32_e32 v154, 16, v154
	v_mfma_f32_32x32x16_bf16 v[48:63], v[176:179], v[236:239], v[48:63]
	ds_read_u16 v177, v162 offset:1632
	ds_read_u16 v178, v162 offset:1904
	ds_read_u16 v127, v163
	ds_read_u16 v124, v163 offset:80
	ds_read_u16 v121, v163 offset:160
	ds_read_u16 v66, v163 offset:240
	ds_read_u16 v64, v163 offset:320
	ds_read_u16 v126, v163 offset:400
	ds_read_u16 v123, v163 offset:480
	ds_read_u16 v120, v163 offset:560
	v_mfma_f32_32x32x16_bf16 v[48:63], v[180:183], v[240:243], v[48:63]
	v_exp_f32_e32 v171, v32
	ds_read_u16 v179, v162 offset:2176
	ds_read_u16 v180, v162 offset:2448
	ds_read_u16 v181, v162 offset:2720
	v_mfma_f32_32x32x16_bf16 v[48:63], v[184:187], v[244:247], v[48:63]
	ds_read_u16 v182, v162 offset:2992
	ds_read_u16 v183, v162 offset:3264
	ds_read_u16 v184, v162 offset:3536
	ds_read_u16 v185, v162 offset:3808
	ds_read_u16 v187, v162 offset:4080
	v_mfma_f32_32x32x16_bf16 v[48:63], v[188:191], v[248:251], v[48:63]
	s_nop 11
	v_exp_f32_e32 v172, v48
	ds_read_u16 v170, v163 offset:640
	ds_read_u16 v169, v163 offset:720
	ds_read_u16 v168, v163 offset:800
	ds_read_u16 v166, v163 offset:880
	ds_read_u16 v125, v163 offset:960
	ds_read_u16 v122, v163 offset:1040
	ds_read_u16 v67, v163 offset:1120
	ds_read_u16 v48, v163 offset:1200
	v_add_f32_e32 v32, 1.0, v172
	v_fma_f32 v172, -v171, v171, 1.0
	v_rcp_f32_e32 v32, v32
	v_sqrt_f32_e32 v172, v172
	s_nop 0
	v_mul_f32_e32 v32, v172, v32
	v_exp_f32_e32 v172, v49
	v_mul_f32_e32 v49, v32, v152
	v_fma_f32 v152, -v33, v33, 1.0
	v_sqrt_f32_e32 v152, v152
	v_add_f32_e32 v32, 1.0, v172
	v_rcp_f32_e32 v32, v32
	v_fmac_f32_e32 v49, 0, v171
	v_mul_f32_e32 v32, v152, v32
	v_mul_f32_e32 v172, v32, v154
	v_add_f32_e32 v32, 1.0, v34
	v_rcp_f32_e32 v32, v32
	v_exp_f32_e32 v34, v50
	v_fmac_f32_e32 v172, v33, v49
	v_mul_f32_e32 v50, v171, v33
	v_mul_f32_e32 v32, v138, v32
	v_exp_f32_e32 v32, v32
	v_add_f32_e32 v33, 1.0, v34
	v_exp_f32_e32 v34, v35
	v_rcp_f32_e32 v33, v33
	v_fma_f32 v35, -v32, v32, 1.0
	v_sqrt_f32_e32 v35, v35
	v_add_f32_e32 v34, 1.0, v34
	v_rcp_f32_e32 v34, v34
	s_waitcnt lgkmcnt(14)
; template <int dir>
; __device__ __forceinline__ void lru_pass(LAS unsigned char* lds, const Params& P, int b, int h, int q, bool dry) {
;     ...
;             float Pp = 1.f, E = 0.f;
; #pragma unroll
;             for (int v = 0; v < 16; ++v) {
;                 const float xcv = __uint_as_float(xcb[v] << 16);
;                 const float r = __builtin_amdgcn_rcpf(1.0f + __builtin_amdgcn_exp2f(zr[v]));
;                 const float ig = __builtin_amdgcn_rcpf(1.0f + __builtin_amdgcn_exp2f(zi[v]));
;                 const float a = __builtin_amdgcn_exp2f(cl * r);
;                 const float sq = __builtin_amdgcn_sqrtf(fmaf(-a, a, 1.0f));
;                 const float u = sq * ig * xcv;
;                 E = fmaf(a, E, u); Pp *= a; zr[v] = E; zi[v] = Pp; }
;             const float Po = __shfl_xor(Pp, 32), Eo = __shfl_xor(E, 32);
;             const float P0 = g ? Po : Pp, E0 = g ? Eo : E, P1 = g ? Pp : Po, E1 = g ? E : Eo;
;             if (g == 0) { AGG[(wid * 2 + 0) * 32 + nl] = P0 * P1; AGG[(wid * 2 + 1) * 32 + nl] = fmaf(P1, E0, E1); }
	v_lshlrev_b32_e32 v152, 16, v155
	v_mul_f32_e32 v33, v35, v33
	v_mul_f32_e32 v173, v33, v152
	v_mul_f32_e32 v34, v138, v34
	v_exp_f32_e32 v33, v51
	v_exp_f32_e32 v34, v34
	v_fmac_f32_e32 v173, v32, v172
	v_mul_f32_e32 v51, v32, v50
	v_exp_f32_e32 v32, v36
	v_add_f32_e32 v33, 1.0, v33
	v_fma_f32 v35, -v34, v34, 1.0
	v_rcp_f32_e32 v33, v33
	v_sqrt_f32_e32 v35, v35
	v_add_f32_e32 v32, 1.0, v32
	v_rcp_f32_e32 v32, v32
	v_lshlrev_b32_e32 v36, 16, v157
	v_mul_f32_e32 v33, v35, v33
	v_mul_f32_e32 v174, v33, v36
	v_mul_f32_e32 v32, v138, v32
	v_fmac_f32_e32 v174, v34, v173
	v_exp_f32_e32 v33, v52
	v_mul_f32_e32 v52, v34, v51
	v_exp_f32_e32 v32, v32
	v_exp_f32_e32 v34, v37
	v_add_f32_e32 v33, 1.0, v33
	v_rcp_f32_e32 v33, v33
	v_fma_f32 v35, -v32, v32, 1.0
	v_add_f32_e32 v34, 1.0, v34
	v_sqrt_f32_e32 v35, v35
	v_rcp_f32_e32 v34, v34
	v_lshlrev_b32_e32 v36, 16, v196
	v_mul_f32_e32 v33, v35, v33
	v_mul_f32_e32 v34, v138, v34
	v_mul_f32_e32 v175, v33, v36
	v_exp_f32_e32 v33, v53
	v_exp_f32_e32 v34, v34
	v_fmac_f32_e32 v175, v32, v174
	v_mul_f32_e32 v53, v32, v52
	v_exp_f32_e32 v32, v38
	v_add_f32_e32 v33, 1.0, v33
	v_fma_f32 v35, -v34, v34, 1.0
	v_rcp_f32_e32 v33, v33
	v_sqrt_f32_e32 v35, v35
	v_add_f32_e32 v32, 1.0, v32
	v_rcp_f32_e32 v32, v32
	v_lshlrev_b32_e32 v36, 16, v197
	v_mul_f32_e32 v33, v35, v33
	v_mul_f32_e32 v176, v33, v36
	v_mul_f32_e32 v32, v138, v32
	v_fmac_f32_e32 v176, v34, v175
	v_exp_f32_e32 v33, v54
	v_mul_f32_e32 v54, v34, v53
	v_exp_f32_e32 v32, v32
	v_exp_f32_e32 v34, v39
	v_add_f32_e32 v33, 1.0, v33
	v_rcp_f32_e32 v33, v33
	v_fma_f32 v35, -v32, v32, 1.0
	v_add_f32_e32 v34, 1.0, v34
	v_sqrt_f32_e32 v35, v35
	v_rcp_f32_e32 v34, v34
	v_lshlrev_b32_e32 v36, 16, v177
	v_mul_f32_e32 v33, v35, v33
	v_mul_f32_e32 v34, v138, v34
	v_mul_f32_e32 v177, v33, v36
	v_exp_f32_e32 v33, v55
	v_exp_f32_e32 v34, v34
	v_fmac_f32_e32 v177, v32, v176
	v_mul_f32_e32 v55, v32, v54
	v_exp_f32_e32 v32, v40
	v_add_f32_e32 v33, 1.0, v33
	v_fma_f32 v35, -v34, v34, 1.0
	v_rcp_f32_e32 v33, v33
	v_sqrt_f32_e32 v35, v35
	v_add_f32_e32 v32, 1.0, v32
	v_rcp_f32_e32 v32, v32
	v_lshlrev_b32_e32 v36, 16, v178
	v_mul_f32_e32 v33, v35, v33
	v_mul_f32_e32 v178, v33, v36
	v_mul_f32_e32 v32, v138, v32
	v_fmac_f32_e32 v178, v34, v177
	v_exp_f32_e32 v33, v56
	v_mul_f32_e32 v56, v34, v55
	v_exp_f32_e32 v32, v32
	v_exp_f32_e32 v34, v41
	v_add_f32_e32 v33, 1.0, v33
	v_rcp_f32_e32 v33, v33
	v_fma_f32 v35, -v32, v32, 1.0
	v_add_f32_e32 v34, 1.0, v34
	v_sqrt_f32_e32 v35, v35
	v_rcp_f32_e32 v34, v34
	v_lshlrev_b32_e32 v36, 16, v179
	v_mul_f32_e32 v33, v35, v33
	v_mul_f32_e32 v34, v138, v34
	v_mul_f32_e32 v179, v33, v36
	v_exp_f32_e32 v33, v57
	v_exp_f32_e32 v34, v34
	v_fmac_f32_e32 v179, v32, v178
	v_mul_f32_e32 v57, v32, v56
	v_exp_f32_e32 v32, v42
	v_add_f32_e32 v33, 1.0, v33
	v_fma_f32 v35, -v34, v34, 1.0
	v_rcp_f32_e32 v33, v33
	v_sqrt_f32_e32 v35, v35
	v_add_f32_e32 v32, 1.0, v32
	v_rcp_f32_e32 v32, v32
	v_lshlrev_b32_e32 v36, 16, v180
	v_mul_f32_e32 v33, v35, v33
	v_mul_f32_e32 v180, v33, v36
	v_mul_f32_e32 v32, v138, v32
	v_fmac_f32_e32 v180, v34, v179
	v_exp_f32_e32 v33, v58
	v_mul_f32_e32 v58, v34, v57
	v_exp_f32_e32 v32, v32
	v_exp_f32_e32 v34, v43
	v_add_f32_e32 v33, 1.0, v33
	v_rcp_f32_e32 v33, v33
	v_fma_f32 v35, -v32, v32, 1.0
	v_add_f32_e32 v34, 1.0, v34
	v_sqrt_f32_e32 v35, v35
	v_rcp_f32_e32 v34, v34
	s_waitcnt lgkmcnt(13)
	v_lshlrev_b32_e32 v36, 16, v181
	v_mul_f32_e32 v33, v35, v33
	v_mul_f32_e32 v34, v138, v34
	v_mul_f32_e32 v181, v33, v36
	v_exp_f32_e32 v33, v59
	v_exp_f32_e32 v34, v34
	v_fmac_f32_e32 v181, v32, v180
	v_mul_f32_e32 v59, v32, v58
	v_exp_f32_e32 v32, v44
	v_add_f32_e32 v33, 1.0, v33
	v_fma_f32 v35, -v34, v34, 1.0
	v_rcp_f32_e32 v33, v33
	v_sqrt_f32_e32 v35, v35
	v_add_f32_e32 v32, 1.0, v32
	v_rcp_f32_e32 v32, v32
	s_waitcnt lgkmcnt(12)
	v_lshlrev_b32_e32 v36, 16, v182
	v_mul_f32_e32 v33, v35, v33
	v_mul_f32_e32 v182, v33, v36
	v_mul_f32_e32 v32, v138, v32
	v_fmac_f32_e32 v182, v34, v181
	v_exp_f32_e32 v33, v60
	v_mul_f32_e32 v60, v34, v59
	v_exp_f32_e32 v32, v32
	v_exp_f32_e32 v34, v45
	v_add_f32_e32 v33, 1.0, v33
	v_rcp_f32_e32 v33, v33
	v_fma_f32 v35, -v32, v32, 1.0
	v_add_f32_e32 v34, 1.0, v34
	v_sqrt_f32_e32 v35, v35
	v_rcp_f32_e32 v34, v34
	s_waitcnt lgkmcnt(11)
	v_lshlrev_b32_e32 v36, 16, v183
	v_mul_f32_e32 v33, v35, v33
	v_mul_f32_e32 v34, v138, v34
	v_mul_f32_e32 v183, v33, v36
	v_exp_f32_e32 v33, v61
	v_exp_f32_e32 v34, v34
	v_fmac_f32_e32 v183, v32, v182
	v_mul_f32_e32 v61, v32, v60
	v_exp_f32_e32 v32, v46
	v_add_f32_e32 v33, 1.0, v33
	v_fma_f32 v35, -v34, v34, 1.0
	v_rcp_f32_e32 v33, v33
	v_sqrt_f32_e32 v35, v35
	v_add_f32_e32 v32, 1.0, v32
	v_rcp_f32_e32 v32, v32
	s_waitcnt lgkmcnt(10)
	v_lshlrev_b32_e32 v36, 16, v184
	v_mul_f32_e32 v33, v35, v33
	v_mul_f32_e32 v184, v33, v36
	v_fmac_f32_e32 v184, v34, v183
	v_exp_f32_e32 v33, v62
	v_mul_f32_e32 v62, v34, v61
	v_mul_f32_e32 v32, v138, v32
	v_exp_f32_e32 v34, v47
	v_exp_f32_e32 v32, v32
	v_add_f32_e32 v33, 1.0, v33
	v_rcp_f32_e32 v33, v33
	v_add_f32_e32 v34, 1.0, v34
	v_fma_f32 v35, -v32, v32, 1.0
	v_rcp_f32_e32 v34, v34
	v_sqrt_f32_e32 v35, v35
	s_waitcnt lgkmcnt(9)
	v_lshlrev_b32_e32 v36, 16, v185
	v_mul_f32_e32 v186, v32, v62
	v_mul_f32_e32 v34, v138, v34
	v_mul_f32_e32 v33, v35, v33
	v_exp_f32_e32 v35, v63
	v_exp_f32_e32 v34, v34
	v_mul_f32_e32 v63, v33, v36
	v_fmac_f32_e32 v63, v32, v184
	v_add_f32_e32 v33, 1.0, v35
	v_fma_f32 v35, -v34, v34, 1.0
	v_rcp_f32_e32 v33, v33
	v_sqrt_f32_e32 v35, v35
	s_waitcnt lgkmcnt(8)
	v_lshlrev_b32_e32 v32, 16, v187
	v_mul_f32_e32 v187, v34, v186
	v_mul_f32_e32 v33, v35, v33
	v_mul_f32_e32 v185, v33, v32
	v_and_b32_e32 v33, 64, v153
	v_xor_b32_e32 v32, 32, v153
	v_add_u32_e32 v33, 64, v33
	v_cmp_lt_i32_e64 s[18:19], v32, v33
	v_fmac_f32_e32 v185, v34, v63
	s_nop 0
	v_cndmask_b32_e64 v32, v153, v32, s[18:19]
	v_lshlrev_b32_e32 v157, 2, v32
	ds_bpermute_b32 v188, v157, v187
	ds_bpermute_b32 v189, v157, v185
	s_and_saveexec_b64 s[18:19], vcc
	s_cbranch_execz .LBB0_299
	s_waitcnt lgkmcnt(0)
	v_fma_f32 v32, v188, v185, v189
	v_mul_f32_e32 v33, v187, v188
	v_add_u32_e32 v35, s98, v147
	ds_write2_b32 v35, v33, v32 offset1:32

; #define LAS __attribute__((address_space(3)))
; template <int dir>
; __device__ __forceinline__ void lru_pass(LAS unsigned char* lds, const Params& P, int b, int h, int q, bool dry) {
;     ...
;             { const int sl = 32 * wid + s_i; const int tlA = dir == 0 ? sl : 255 - sl;
;               const LAS unsigned char* ap = XC + tlA * XC_PITCH + 16 * g;
;               const LAS unsigned char* wrp = WB + nl * XC_PITCH + 16 * g; const LAS unsigned char* wip = wrp + 32 * XC_PITCH;
; #pragma unroll
;               for (int ks = 0; ks < 8; ++ks) { const bf16x8 A = *(const LAS bf16x8*)(ap + 32 * ks);
;                   const bf16x8 Br = *(const LAS bf16x8*)(wrp + 32 * ks), Bi = *(const LAS bf16x8*)(wip + 32 * ks);
;                   zr = __builtin_amdgcn_mfma_f32_32x32x16_bf16(A, Br, zr, 0, 0, 0); zi = __builtin_amdgcn_mfma_f32_32x32x16_bf16(A, Bi, zi, 0, 0, 0); } }
;             unsigned xcb[16], pk[16];
; #pragma unroll
;             for (int v = 0; v < 16; ++v) { const int s = sbase + v; const int tl = dir == 0 ? s : 255 - s; xcb[v] = *(const LAS bf16_t*)(XC + tl * XC_PITCH + chl * 2);
;                 if (dir == 0) pk[v] = *(const LAS bf16_t*)(TIN + tl * IO_NP + nl * 2); else pk[v] = *(const LAS unsigned*)(TIN + tl * IO_WP + nl * 4); }
;             float Pp = 1.f, E = 0.f;
; #pragma unroll
;             for (int v = 0; v < 16; ++v) {
;                 const float xcv = __uint_as_float(xcb[v] << 16);
;                 const float r = __builtin_amdgcn_rcpf(1.0f + __builtin_amdgcn_exp2f(zr[v]));
;                 const float ig = __builtin_amdgcn_rcpf(1.0f + __builtin_amdgcn_exp2f(zi[v]));
;                 const float a = __builtin_amdgcn_exp2f(cl * r);
;                 const float sq = __builtin_amdgcn_sqrtf(fmaf(-a, a, 1.0f));
;                 const float u = sq * ig * xcv;
;                 E = fmaf(a, E, u); Pp *= a; zr[v] = E; zi[v] = Pp; }
.LBB0_311:
	ds_read_b128 v[128:131], v172
	ds_read_b128 v[48:51], v173
	ds_read_b128 v[132:135], v172 offset:32
	ds_read_b128 v[52:55], v173 offset:32
	s_waitcnt lgkmcnt(2)
	v_mfma_f32_32x32x16_bf16 v[32:47], v[128:131], v[48:51], v[0:15]
	s_waitcnt lgkmcnt(0)
	v_mfma_f32_32x32x16_bf16 v[32:47], v[132:135], v[52:55], v[32:47]
	ds_read_b128 v[224:227], v172 offset:64
	ds_read_b128 v[48:51], v173 offset:64
	ds_read_b128 v[228:231], v172 offset:96
	ds_read_b128 v[52:55], v173 offset:96
	s_waitcnt lgkmcnt(2)
	v_mfma_f32_32x32x16_bf16 v[32:47], v[224:227], v[48:51], v[32:47]
	s_waitcnt lgkmcnt(0)
	v_mfma_f32_32x32x16_bf16 v[32:47], v[228:231], v[52:55], v[32:47]
	ds_read_b128 v[232:235], v172 offset:128
	ds_read_b128 v[48:51], v173 offset:128
	ds_read_b128 v[236:239], v172 offset:160
	ds_read_b128 v[52:55], v173 offset:160
	s_waitcnt lgkmcnt(2)
	v_mfma_f32_32x32x16_bf16 v[32:47], v[232:235], v[48:51], v[32:47]
	s_waitcnt lgkmcnt(0)
	v_mfma_f32_32x32x16_bf16 v[32:47], v[236:239], v[52:55], v[32:47]
	ds_read_b128 v[240:243], v172 offset:192
	ds_read_b128 v[48:51], v173 offset:192
	ds_read_b128 v[244:247], v172 offset:224
	ds_read_b128 v[52:55], v173 offset:224
	ds_read_b128 v[248:251], v173 offset:8704
	ds_read_b128 v[146:149], v173 offset:8736
	s_waitcnt lgkmcnt(4)
	v_mfma_f32_32x32x16_bf16 v[32:47], v[240:243], v[48:51], v[32:47]
	s_waitcnt lgkmcnt(2)
	v_mfma_f32_32x32x16_bf16 v[32:47], v[244:247], v[52:55], v[32:47]
	s_waitcnt lgkmcnt(1)
	v_mfma_f32_32x32x16_bf16 v[48:63], v[128:131], v[248:251], v[16:31]
	s_setprio 0
	s_nop 9
	v_exp_f32_e32 v32, v32
	v_exp_f32_e32 v33, v33
	v_exp_f32_e32 v34, v34
	v_add_f32_e32 v32, 1.0, v32
	v_rcp_f32_e32 v32, v32
	v_add_f32_e32 v33, 1.0, v33
	s_waitcnt lgkmcnt(0)
	v_mfma_f32_32x32x16_bf16 v[48:63], v[132:135], v[146:149], v[48:63]
	ds_read_b128 v[128:131], v173 offset:8768
	ds_read_b128 v[132:135], v173 offset:8800
	v_mul_f32_e32 v32, v159, v32
	v_rcp_f32_e32 v33, v33
	s_nop 0
	v_mul_f32_e32 v33, v159, v33
	s_waitcnt lgkmcnt(1)
	v_mfma_f32_32x32x16_bf16 v[48:63], v[224:227], v[128:131], v[48:63]
	v_exp_f32_e32 v227, v32
	v_exp_f32_e32 v33, v33
	s_waitcnt lgkmcnt(0)
	v_mfma_f32_32x32x16_bf16 v[48:63], v[228:231], v[132:135], v[48:63]
	ds_read_b128 v[128:131], v173 offset:8832
	ds_read_b128 v[132:135], v173 offset:8864
	ds_read_b128 v[146:149], v173 offset:8896
	ds_read_b128 v[228:231], v173 offset:8928
	s_waitcnt lgkmcnt(3)
	v_mfma_f32_32x32x16_bf16 v[48:63], v[232:235], v[128:131], v[48:63]
	ds_read_u16 v162, v174
	ds_read_b32 v226, v175
	ds_read_u16 v163, v176
	ds_read_b32 v225, v177
	ds_read_u16 v232, v178
	ds_read_b32 v224, v179
	ds_read_u16 v233, v180
	ds_read_b32 v223, v181
	s_waitcnt lgkmcnt(7)
	v_lshlrev_b32_e32 v162, 16, v162
	s_waitcnt lgkmcnt(5)
	v_lshlrev_b32_e32 v163, 16, v163
	v_mfma_f32_32x32x16_bf16 v[48:63], v[236:239], v[132:135], v[48:63]
	ds_read_u16 v234, v182
	ds_read_b32 v135, v183
	ds_read_u16 v235, v184
	ds_read_b32 v134, v185
	ds_read_u16 v236, v186
	ds_read_b32 v133, v187
	ds_read_u16 v237, v188
	ds_read_b32 v131, v189
	v_mfma_f32_32x32x16_bf16 v[48:63], v[240:243], v[146:149], v[48:63]
	ds_read_u16 v146, v190
	ds_read_b32 v132, v191
	ds_read_u16 v147, v192
	ds_read_b32 v130, v193
	ds_read_u16 v148, v194
	ds_read_b32 v129, v195
	ds_read_u16 v149, v196
	ds_read_b32 v128, v197
	v_mfma_f32_32x32x16_bf16 v[48:63], v[244:247], v[228:231], v[48:63]
	s_nop 11
	v_exp_f32_e32 v228, v48
	ds_read_u16 v239, v198
	ds_read_b32 v67, v199
	ds_read_u16 v240, v200
	ds_read_b32 v66, v201
	ds_read_u16 v241, v202
	ds_read_b32 v64, v203
	ds_read_u16 v242, v204
	ds_read_b32 v48, v205
	v_add_f32_e32 v32, 1.0, v228
	v_fma_f32 v228, -v227, v227, 1.0
	v_rcp_f32_e32 v32, v32
	v_sqrt_f32_e32 v228, v228
	s_nop 0
	v_mul_f32_e32 v32, v228, v32
	v_exp_f32_e32 v228, v49
	v_mul_f32_e32 v49, v32, v162
	v_fma_f32 v162, -v33, v33, 1.0
	v_sqrt_f32_e32 v162, v162
	v_add_f32_e32 v32, 1.0, v228
	v_rcp_f32_e32 v32, v32
	v_fmac_f32_e32 v49, 0, v227
	v_mul_f32_e32 v32, v162, v32
	v_mul_f32_e32 v228, v32, v163
	v_add_f32_e32 v32, 1.0, v34
	v_rcp_f32_e32 v32, v32
	v_exp_f32_e32 v34, v50
	v_fmac_f32_e32 v228, v33, v49
	v_mul_f32_e32 v50, v227, v33
	v_mul_f32_e32 v32, v159, v32
	v_exp_f32_e32 v32, v32
	v_add_f32_e32 v33, 1.0, v34
	v_exp_f32_e32 v34, v35
	v_rcp_f32_e32 v33, v33
	v_fma_f32 v35, -v32, v32, 1.0
	v_sqrt_f32_e32 v35, v35
	v_add_f32_e32 v34, 1.0, v34
	v_rcp_f32_e32 v34, v34
	s_waitcnt lgkmcnt(14)
; template <int dir>
; __device__ __forceinline__ void lru_pass(LAS unsigned char* lds, const Params& P, int b, int h, int q, bool dry) {
;     ...
;             float Pp = 1.f, E = 0.f;
; #pragma unroll
;             for (int v = 0; v < 16; ++v) {
;                 const float xcv = __uint_as_float(xcb[v] << 16);
;                 const float r = __builtin_amdgcn_rcpf(1.0f + __builtin_amdgcn_exp2f(zr[v]));
;                 const float ig = __builtin_amdgcn_rcpf(1.0f + __builtin_amdgcn_exp2f(zi[v]));
;                 const float a = __builtin_amdgcn_exp2f(cl * r);
;                 const float sq = __builtin_amdgcn_sqrtf(fmaf(-a, a, 1.0f));
;                 const float u = sq * ig * xcv;
;                 E = fmaf(a, E, u); Pp *= a; zr[v] = E; zi[v] = Pp; }
;             const float Po = __shfl_xor(Pp, 32), Eo = __shfl_xor(E, 32);
;             const float P0 = g ? Po : Pp, E0 = g ? Eo : E, P1 = g ? Pp : Po, E1 = g ? E : Eo;
;             if (g == 0) { AGG[(wid * 2 + 0) * 32 + nl] = P0 * P1; AGG[(wid * 2 + 1) * 32 + nl] = fmaf(P1, E0, E1); }
	v_lshlrev_b32_e32 v162, 16, v232
	v_mul_f32_e32 v33, v35, v33
	v_mul_f32_e32 v229, v33, v162
	v_mul_f32_e32 v34, v159, v34
	v_exp_f32_e32 v33, v51
	v_exp_f32_e32 v34, v34
	v_fmac_f32_e32 v229, v32, v228
	v_mul_f32_e32 v51, v32, v50
	v_exp_f32_e32 v32, v36
	v_add_f32_e32 v33, 1.0, v33
	v_fma_f32 v35, -v34, v34, 1.0
	v_rcp_f32_e32 v33, v33
	v_sqrt_f32_e32 v35, v35
	v_add_f32_e32 v32, 1.0, v32
	v_rcp_f32_e32 v32, v32
	v_lshlrev_b32_e32 v36, 16, v233
	v_mul_f32_e32 v33, v35, v33
	v_mul_f32_e32 v230, v33, v36
	v_mul_f32_e32 v32, v159, v32
	v_fmac_f32_e32 v230, v34, v229
	v_exp_f32_e32 v33, v52
	v_mul_f32_e32 v52, v34, v51
	v_exp_f32_e32 v32, v32
	v_exp_f32_e32 v34, v37
	v_add_f32_e32 v33, 1.0, v33
	v_rcp_f32_e32 v33, v33
	v_fma_f32 v35, -v32, v32, 1.0
	v_add_f32_e32 v34, 1.0, v34
	v_sqrt_f32_e32 v35, v35
	v_rcp_f32_e32 v34, v34
	v_lshlrev_b32_e32 v36, 16, v234
	v_mul_f32_e32 v33, v35, v33
	v_mul_f32_e32 v34, v159, v34
	v_mul_f32_e32 v231, v33, v36
	v_exp_f32_e32 v33, v53
	v_exp_f32_e32 v34, v34
	v_fmac_f32_e32 v231, v32, v230
	v_mul_f32_e32 v53, v32, v52
	v_exp_f32_e32 v32, v38
	v_add_f32_e32 v33, 1.0, v33
	v_fma_f32 v35, -v34, v34, 1.0
	v_rcp_f32_e32 v33, v33
	v_sqrt_f32_e32 v35, v35
	v_add_f32_e32 v32, 1.0, v32
	v_rcp_f32_e32 v32, v32
	v_lshlrev_b32_e32 v36, 16, v235
	v_mul_f32_e32 v33, v35, v33
	v_mul_f32_e32 v232, v33, v36
	v_mul_f32_e32 v32, v159, v32
	v_fmac_f32_e32 v232, v34, v231
	v_exp_f32_e32 v33, v54
	v_mul_f32_e32 v54, v34, v53
	v_exp_f32_e32 v32, v32
	v_exp_f32_e32 v34, v39
	v_add_f32_e32 v33, 1.0, v33
	v_rcp_f32_e32 v33, v33
	v_fma_f32 v35, -v32, v32, 1.0
	v_add_f32_e32 v34, 1.0, v34
	v_sqrt_f32_e32 v35, v35
	v_rcp_f32_e32 v34, v34
	v_lshlrev_b32_e32 v36, 16, v236
	v_mul_f32_e32 v33, v35, v33
	v_mul_f32_e32 v34, v159, v34
	v_mul_f32_e32 v233, v33, v36
	v_exp_f32_e32 v33, v55
	v_exp_f32_e32 v34, v34
	v_fmac_f32_e32 v233, v32, v232
	v_mul_f32_e32 v55, v32, v54
	v_exp_f32_e32 v32, v40
	v_add_f32_e32 v33, 1.0, v33
	v_fma_f32 v35, -v34, v34, 1.0
	v_rcp_f32_e32 v33, v33
	v_sqrt_f32_e32 v35, v35
	v_add_f32_e32 v32, 1.0, v32
	v_rcp_f32_e32 v32, v32
	v_lshlrev_b32_e32 v36, 16, v237
	v_mul_f32_e32 v33, v35, v33
	v_mul_f32_e32 v234, v33, v36
	v_mul_f32_e32 v32, v159, v32
	v_fmac_f32_e32 v234, v34, v233
	v_exp_f32_e32 v33, v56
	v_mul_f32_e32 v56, v34, v55
	v_exp_f32_e32 v32, v32
	v_exp_f32_e32 v34, v41
	v_add_f32_e32 v33, 1.0, v33
	v_rcp_f32_e32 v33, v33
	v_fma_f32 v35, -v32, v32, 1.0
	v_add_f32_e32 v34, 1.0, v34
	v_sqrt_f32_e32 v35, v35
	v_rcp_f32_e32 v34, v34
	v_lshlrev_b32_e32 v36, 16, v146
	v_mul_f32_e32 v33, v35, v33
	v_mul_f32_e32 v34, v159, v34
	v_mul_f32_e32 v235, v33, v36
	v_exp_f32_e32 v33, v57
	v_exp_f32_e32 v34, v34
	v_fmac_f32_e32 v235, v32, v234
	v_mul_f32_e32 v57, v32, v56
	v_exp_f32_e32 v32, v42
	v_add_f32_e32 v33, 1.0, v33
	v_fma_f32 v35, -v34, v34, 1.0
	v_rcp_f32_e32 v33, v33
	v_sqrt_f32_e32 v35, v35
	v_add_f32_e32 v32, 1.0, v32
	v_rcp_f32_e32 v32, v32
	s_waitcnt lgkmcnt(13)
	v_lshlrev_b32_e32 v36, 16, v147
	v_mul_f32_e32 v33, v35, v33
	v_mul_f32_e32 v236, v33, v36
	v_mul_f32_e32 v32, v159, v32
	v_fmac_f32_e32 v236, v34, v235
	v_exp_f32_e32 v33, v58
	v_mul_f32_e32 v58, v34, v57
	v_exp_f32_e32 v32, v32
	v_exp_f32_e32 v34, v43
	v_add_f32_e32 v33, 1.0, v33
	v_rcp_f32_e32 v33, v33
	v_fma_f32 v35, -v32, v32, 1.0
	v_add_f32_e32 v34, 1.0, v34
	v_sqrt_f32_e32 v35, v35
	v_rcp_f32_e32 v34, v34
	s_waitcnt lgkmcnt(11)
	v_lshlrev_b32_e32 v36, 16, v148
	v_mul_f32_e32 v33, v35, v33
	v_mul_f32_e32 v34, v159, v34
	v_mul_f32_e32 v237, v33, v36
	v_exp_f32_e32 v33, v59
	v_exp_f32_e32 v34, v34
	v_fmac_f32_e32 v237, v32, v236
	v_mul_f32_e32 v59, v32, v58
	v_exp_f32_e32 v32, v44
	v_add_f32_e32 v33, 1.0, v33
	v_fma_f32 v35, -v34, v34, 1.0
	v_rcp_f32_e32 v33, v33
	v_sqrt_f32_e32 v35, v35
	v_add_f32_e32 v32, 1.0, v32
	v_rcp_f32_e32 v32, v32
	s_waitcnt lgkmcnt(9)
	v_lshlrev_b32_e32 v36, 16, v149
	v_mul_f32_e32 v33, v35, v33
	v_mul_f32_e32 v238, v33, v36
	v_mul_f32_e32 v32, v159, v32
	v_fmac_f32_e32 v238, v34, v237
	v_exp_f32_e32 v33, v60
	v_mul_f32_e32 v60, v34, v59
	v_exp_f32_e32 v32, v32
	v_exp_f32_e32 v34, v45
	v_add_f32_e32 v33, 1.0, v33
	v_rcp_f32_e32 v33, v33
	v_fma_f32 v35, -v32, v32, 1.0
	v_add_f32_e32 v34, 1.0, v34
	v_sqrt_f32_e32 v35, v35
	v_rcp_f32_e32 v34, v34
	s_waitcnt lgkmcnt(7)
	v_lshlrev_b32_e32 v36, 16, v239
	v_mul_f32_e32 v33, v35, v33
	v_mul_f32_e32 v34, v159, v34
	v_mul_f32_e32 v239, v33, v36
	v_exp_f32_e32 v33, v61
	v_exp_f32_e32 v34, v34
	v_fmac_f32_e32 v239, v32, v238
	v_mul_f32_e32 v61, v32, v60
	v_exp_f32_e32 v32, v46
	v_add_f32_e32 v33, 1.0, v33
	v_fma_f32 v35, -v34, v34, 1.0
	v_rcp_f32_e32 v33, v33
	v_sqrt_f32_e32 v35, v35
	v_add_f32_e32 v32, 1.0, v32
	v_rcp_f32_e32 v32, v32
	s_waitcnt lgkmcnt(5)
	v_lshlrev_b32_e32 v36, 16, v240
	v_mul_f32_e32 v33, v35, v33
	v_mul_f32_e32 v240, v33, v36
	v_fmac_f32_e32 v240, v34, v239
	v_exp_f32_e32 v33, v62
	v_mul_f32_e32 v62, v34, v61
	v_mul_f32_e32 v32, v159, v32
	v_exp_f32_e32 v34, v47
	v_exp_f32_e32 v32, v32
	v_add_f32_e32 v33, 1.0, v33
	v_rcp_f32_e32 v33, v33
	v_add_f32_e32 v34, 1.0, v34
	v_fma_f32 v35, -v32, v32, 1.0
	v_rcp_f32_e32 v34, v34
	v_sqrt_f32_e32 v35, v35
	s_waitcnt lgkmcnt(3)
	v_lshlrev_b32_e32 v36, 16, v241
	v_mul_f32_e32 v243, v32, v62
	v_mul_f32_e32 v34, v159, v34
	v_mul_f32_e32 v33, v35, v33
	v_exp_f32_e32 v35, v63
	v_exp_f32_e32 v34, v34
	v_mul_f32_e32 v63, v33, v36
	v_fmac_f32_e32 v63, v32, v240
	v_add_f32_e32 v33, 1.0, v35
	v_fma_f32 v35, -v34, v34, 1.0
	v_rcp_f32_e32 v33, v33
	v_sqrt_f32_e32 v35, v35
	s_waitcnt lgkmcnt(1)
	v_lshlrev_b32_e32 v32, 16, v242
	v_mul_f32_e32 v242, v34, v243
	ds_bpermute_b32 v244, v157, v242
	v_mul_f32_e32 v33, v35, v33
	v_mul_f32_e32 v241, v33, v32
	v_fmac_f32_e32 v241, v34, v63
	ds_bpermute_b32 v245, v157, v241
	s_and_saveexec_b64 s[18:19], vcc
	s_cbranch_execz .LBB0_313
	s_waitcnt lgkmcnt(0)
	v_fma_f32 v32, v244, v241, v245
	v_mul_f32_e32 v33, v242, v244
	v_add_u32_e32 v35, s98, v254
	ds_write2_b32 v35, v33, v32 offset1:32
